# v18: v12 + ffn_out epilogue: LN1 affine vectors g,b (column half 0) loaded once per tile instead of once per row group (28 redundant loads and their waits removed)
# speedup vs baseline: 1.0034x; 1.0034x over previous
; __device__ __forceinline__ u32x4 pk8h(const f32x4 a, const f32x4 b) { u32x4 w; w.x = pkh(a[0], a[1]); w.y = pkh(a[2], a[3]); w.z = pkh(b[0], b[1]); w.w = pkh(b[2], b[3]); return w; }
; __device__ __forceinline__ f32x4 h4lo(const u32x4 w) { return (f32x4){hlo(w.x), hhi(w.x), hlo(w.y), hhi(w.y)}; }
; __device__ __forceinline__ f32x4 h4hi(const u32x4 w) { return (f32x4){hlo(w.z), hhi(w.z), hlo(w.w), hhi(w.w)}; }
;     __device__ __forceinline__ void operator()(const i32x4 (&acc)[2][2][4][2], const Unit& u, int wr, int wc, int fr, int fq) const {
;         const int row0 = u.pm * BM + wr * 64 + fr, col0 = u.pn * BM + wc * 32 + 8 * fq;
;         const float wdq = __builtin_bit_cast(float, *wmax_bits) * (1.0f / 127.0f);
; #pragma unroll
;         for (int ai = 0; ai < 2; ++ai) {
;             u32x4 y[4][2]; float mean[4], rstd[4], f[4];
; #pragma unroll
;             for (int m = 0; m < 4; ++m) { const int row = row0 + ai * HALF + m * 16; const bf16_t* yp = X + (size_t)row * 4096 + col0; y[m][0] = *(const u32x4*)yp; y[m][1] = *(const u32x4*)(yp + HALF);
;                 mean[m] = stats[2 * row]; rstd[m] = stats[2 * row + 1]; f[m] = rowinv[row] * wdq; }
; #pragma unroll
;             for (int m = 0; m < 4; ++m) { bf16_t* rowp = X + (size_t)(row0 + ai * HALF + m * 16) * 4096 + col0;
; #pragma unroll
;                 for (int bj = 0; bj < 2; ++bj) { const int c = col0 + bj * HALF; const float ra = rstd[m] * alpha;
;                     const f32x4 g0 = *(const f32x4*)(g + c) * ra, g1 = *(const f32x4*)(g + c + 4) * ra, b0 = *(const f32x4*)(b + c) * alpha, b1 = *(const f32x4*)(b + c + 4) * alpha;
;                     const i32x4 a0 = acc[ai][bj][m][0], a1 = acc[ai][bj][m][1];
;                     f32x4 q0, q1; q0.x = (float)a0.x; q0.y = (float)a0.y; q0.z = (float)a0.z; q0.w = (float)a0.w; q1.x = (float)a1.x; q1.y = (float)a1.y; q1.z = (float)a1.z; q1.w = (float)a1.w;
;                     *(u32x4*)(rowp + bj * HALF) = pk8h((h4lo(y[m][bj]) - mean[m]) * g0 + b0 + q0 * f[m], (h4hi(y[m][bj]) - mean[m]) * g1 + b1 + q1 * f[m]); } }
.LBB0_1203:
	v_lshl_add_u32 v150, s85, 8, v1
	v_lshl_or_b32 v142, s83, 8, v157
	v_lshlrev_b32_e32 v140, 1, v150
	v_ashrrev_i32_e32 v143, 31, v142
	v_ashrrev_i32_e32 v141, 31, v140
	v_ashrrev_i32_e32 v151, 31, v150
	v_lshl_add_u64 v[140:141], v[140:141], 2, s[36:37]
	v_lshlrev_b64 v[146:147], 2, v[142:143]
	v_lshlrev_b64 v[144:145], 1, v[142:143]
	global_load_dword v185, v183, s[16:17]
	v_lshl_add_u64 v[148:149], v[150:151], 2, s[14:15]
	global_load_dwordx2 v[154:155], v[140:141], off
	global_load_dword v186, v[148:149], off
	v_lshl_add_u64 v[140:141], s[44:45], 0, v[146:147]
	v_lshl_add_u64 v[142:143], s[42:43], 0, v[146:147]
	v_lshl_add_u64 v[146:147], s[10:11], 0, v[144:145]
	v_lshlrev_b64 v[180:181], 13, v[150:151]
	v_lshl_add_u64 v[198:199], v[146:147], 0, v[180:181]
	global_load_dwordx4 v[234:237], v[140:141], off offset:16
	global_load_dwordx4 v[238:241], v[140:141], off
	global_load_dwordx4 v[242:245], v[142:143], off offset:16
	global_load_dwordx4 v[246:249], v[142:143], off
	global_load_dwordx4 v[176:179], v[198:199], off
	v_or_b32_e32 v210, 16, v150
	v_or_b32_e32 v152, 32, v150
	v_cvt_f32_i32_e32 v202, v126
	v_cvt_f32_i32_e32 v206, v122
	v_cvt_f32_i32_e32 v208, v124
	v_or_b32_e32 v126, 48, v150
	v_lshlrev_b32_e32 v122, 1, v210
	v_lshlrev_b32_e32 v124, 1, v152
	v_cvt_f32_i32_e32 v204, v128
	v_cvt_f32_i32_e32 v207, v123
	v_cvt_f32_i32_e32 v209, v125
	v_ashrrev_i32_e32 v211, 31, v210
	v_ashrrev_i32_e32 v153, 31, v152
	v_lshlrev_b32_e32 v128, 1, v126
	v_ashrrev_i32_e32 v123, 31, v122
	v_ashrrev_i32_e32 v125, 31, v124
	v_cvt_f32_i32_e32 v203, v127
	v_cvt_f32_i32_e32 v205, v129
	v_ashrrev_i32_e32 v127, 31, v126
	v_lshl_add_u64 v[226:227], v[210:211], 2, s[14:15]
	v_lshl_add_u64 v[228:229], v[152:153], 2, s[14:15]
	v_ashrrev_i32_e32 v129, 31, v128
	v_lshl_add_u64 v[122:123], v[122:123], 2, s[36:37]
	v_lshl_add_u64 v[124:125], v[124:125], 2, s[36:37]
	v_lshl_add_u64 v[230:231], v[126:127], 2, s[14:15]
	v_lshl_add_u64 v[232:233], v[128:129], 2, s[36:37]
	global_load_dwordx4 v[198:201], v[198:199], off offset:256
	s_nop 0
	global_load_dwordx2 v[128:129], v[122:123], off
	global_load_dword v189, v[226:227], off
	s_nop 0
	global_load_dwordx2 v[124:125], v[124:125], off
	s_nop 0
	global_load_dword v192, v[228:229], off
	global_load_dwordx2 v[122:123], v[232:233], off
	global_load_dword v159, v[230:231], off
	v_lshl_add_u64 v[180:181], s[10:11], 0, v[180:181]
	v_lshl_add_u64 v[180:181], v[180:181], 0, v[144:145]
	v_cvt_f32_i32_e32 v119, v119
	v_cvt_f32_i32_e32 v118, v118
	v_cvt_f32_i32_e32 v121, v121
	v_cvt_f32_i32_e32 v120, v120
	v_cvt_f32_i32_e32 v111, v111
	v_cvt_f32_i32_e32 v110, v110
	v_cvt_f32_i32_e32 v113, v113
	v_cvt_f32_i32_e32 v112, v112
	v_cvt_f32_i32_e32 v103, v103
	v_cvt_f32_i32_e32 v102, v102
	v_cvt_f32_i32_e32 v105, v105
	v_cvt_f32_i32_e32 v104, v104
	v_lshlrev_b64 v[152:153], 13, v[152:153]
	v_cvt_f32_i32_e32 v95, v95
	v_cvt_f32_i32_e32 v94, v94
	v_cvt_f32_i32_e32 v97, v97
	v_cvt_f32_i32_e32 v96, v96
	v_cvt_f32_i32_e32 v87, v87
	v_cvt_f32_i32_e32 v86, v86
	v_cvt_f32_i32_e32 v89, v89
	v_cvt_f32_i32_e32 v88, v88
	v_cvt_f32_i32_e32 v79, v79
	v_cvt_f32_i32_e32 v78, v78
	v_cvt_f32_i32_e32 v81, v81
	v_cvt_f32_i32_e32 v80, v80
	v_cvt_f32_i32_e32 v71, v71
	v_cvt_f32_i32_e32 v70, v70
	v_cvt_f32_i32_e32 v73, v73
	v_cvt_f32_i32_e32 v72, v72
	v_cvt_f32_i32_e32 v67, v67
	v_cvt_f32_i32_e32 v66, v66
	v_cvt_f32_i32_e32 v69, v69
	v_cvt_f32_i32_e32 v68, v68
	v_cvt_f32_i32_e32 v55, v55
	v_cvt_f32_i32_e32 v54, v54
	v_cvt_f32_i32_e32 v57, v57
	v_cvt_f32_i32_e32 v56, v56
	v_cvt_f32_i32_e32 v51, v51
	v_cvt_f32_i32_e32 v50, v50
	v_cvt_f32_i32_e32 v53, v53
	s_waitcnt vmcnt(0)
	v_mul_f32_e32 v151, 0x3c010204, v185
	v_mul_f32_e32 v190, 0x3fb504f3, v155
	v_mul_f32_e32 v186, v151, v186
	v_cvt_f32_i32_e32 v52, v52
	v_cvt_f32_i32_e32 v47, v47
	v_cvt_f32_i32_e32 v46, v46
	v_cvt_f32_i32_e32 v49, v49
	v_pk_mul_f32 v[162:163], v[236:237], s[90:91] op_sel_hi:[1,0]
	v_pk_mul_f32 v[166:167], v[240:241], s[90:91] op_sel_hi:[1,0]
	v_pk_mul_f32 v[164:165], v[238:239], s[90:91] op_sel_hi:[1,0]
	v_cvt_f32_f16_sdwa v155, v176 dst_sel:DWORD dst_unused:UNUSED_PAD src0_sel:WORD_1
	v_cvt_f32_f16_e32 v185, v176
	v_cvt_f32_f16_sdwa v225, v177 dst_sel:DWORD dst_unused:UNUSED_PAD src0_sel:WORD_1
	v_cvt_f32_f16_e32 v176, v177
	v_cvt_f32_f16_sdwa v229, v178 dst_sel:DWORD dst_unused:UNUSED_PAD src0_sel:WORD_1
	v_cvt_f32_f16_e32 v228, v178
	v_cvt_f32_f16_sdwa v227, v179 dst_sel:DWORD dst_unused:UNUSED_PAD src0_sel:WORD_1
	v_cvt_f32_f16_e32 v226, v179
	v_pk_mul_f32 v[160:161], v[234:235], s[90:91] op_sel_hi:[1,0]
	v_pk_mul_f32 v[174:175], v[190:191], v[248:249] op_sel_hi:[0,1]
	v_pk_mul_f32 v[172:173], v[190:191], v[246:247] op_sel_hi:[0,1]
	v_pk_mul_f32 v[170:171], v[190:191], v[244:245] op_sel_hi:[0,1]
	v_pk_mul_f32 v[168:169], v[190:191], v[242:243] op_sel_hi:[0,1]
	v_sub_f32_e32 v176, v176, v154
	v_sub_f32_e32 v177, v225, v154
	v_sub_f32_e32 v178, v185, v154
	v_sub_f32_e32 v179, v155, v154
	v_sub_f32_e32 v226, v226, v154
	v_sub_f32_e32 v227, v227, v154
	v_sub_f32_e32 v228, v228, v154
	v_sub_f32_e32 v229, v229, v154
	v_pk_fma_f32 v[164:165], v[178:179], v[172:173], v[164:165]
	v_pk_fma_f32 v[166:167], v[176:177], v[174:175], v[166:167]
	v_pk_fma_f32 v[160:161], v[228:229], v[168:169], v[160:161]
	v_pk_fma_f32 v[162:163], v[226:227], v[170:171], v[162:163]
	v_pk_fma_f32 v[166:167], v[186:187], v[204:205], v[166:167] op_sel_hi:[0,1,1]
	v_pk_fma_f32 v[164:165], v[186:187], v[202:203], v[164:165] op_sel_hi:[0,1,1]
	v_pk_fma_f32 v[168:169], v[186:187], v[208:209], v[162:163] op_sel_hi:[0,1,1]
	v_pk_fma_f32 v[162:163], v[186:187], v[206:207], v[160:161] op_sel_hi:[0,1,1]
; __device__ __forceinline__ u32x4 pk8h(const f32x4 a, const f32x4 b) { u32x4 w; w.x = pkh(a[0], a[1]); w.y = pkh(a[2], a[3]); w.z = pkh(b[0], b[1]); w.w = pkh(b[2], b[3]); return w; }
; __device__ __forceinline__ f32x4 h4lo(const u32x4 w) { return (f32x4){hlo(w.x), hhi(w.x), hlo(w.y), hhi(w.y)}; }
; __device__ __forceinline__ f32x4 h4hi(const u32x4 w) { return (f32x4){hlo(w.z), hhi(w.z), hlo(w.w), hhi(w.w)}; }
;     __device__ __forceinline__ void operator()(const i32x4 (&acc)[2][2][4][2], const Unit& u, int wr, int wc, int fr, int fq) const {
;     ...
;             for (int m = 0; m < 4; ++m) { const int row = row0 + ai * HALF + m * 16; const bf16_t* yp = X + (size_t)row * 4096 + col0; y[m][0] = *(const u32x4*)yp; y[m][1] = *(const u32x4*)(yp + HALF);
;                 mean[m] = stats[2 * row]; rstd[m] = stats[2 * row + 1]; f[m] = rowinv[row] * wdq; }
; #pragma unroll
;             for (int m = 0; m < 4; ++m) { bf16_t* rowp = X + (size_t)(row0 + ai * HALF + m * 16) * 4096 + col0;
; #pragma unroll
;                 for (int bj = 0; bj < 2; ++bj) { const int c = col0 + bj * HALF; const float ra = rstd[m] * alpha;
;                     const f32x4 g0 = *(const f32x4*)(g + c) * ra, g1 = *(const f32x4*)(g + c + 4) * ra, b0 = *(const f32x4*)(b + c) * alpha, b1 = *(const f32x4*)(b + c + 4) * alpha;
;                     const i32x4 a0 = acc[ai][bj][m][0], a1 = acc[ai][bj][m][1];
;                     f32x4 q0, q1; q0.x = (float)a0.x; q0.y = (float)a0.y; q0.z = (float)a0.z; q0.w = (float)a0.w; q1.x = (float)a1.x; q1.y = (float)a1.y; q1.z = (float)a1.z; q1.w = (float)a1.w;
;                     *(u32x4*)(rowp + bj * HALF) = pk8h((h4lo(y[m][bj]) - mean[m]) * g0 + b0 + q0 * f[m], (h4hi(y[m][bj]) - mean[m]) * g1 + b1 + q1 * f[m]); } }
	v_cvt_pk_f16_f32 v160, v164, v165
	v_cvt_pk_f16_f32 v161, v166, v167
	v_cvt_pk_f16_f32 v162, v162, v163
	v_cvt_pk_f16_f32 v163, v168, v169
	global_store_dwordx4 v[180:181], v[160:163], off
	global_load_dwordx4 v[160:163], v[142:143], off offset:512
	s_nop 0
	global_load_dwordx4 v[164:167], v[142:143], off offset:528
	global_load_dwordx4 v[168:171], v[140:141], off offset:512
	global_load_dwordx4 v[172:175], v[140:141], off offset:528
	v_lshlrev_b64 v[202:203], 13, v[210:211]
	v_cvt_f32_f16_sdwa v155, v198 dst_sel:DWORD dst_unused:UNUSED_PAD src0_sel:WORD_1
	v_cvt_f32_f16_e32 v185, v198
	v_cvt_f32_f16_sdwa v206, v199 dst_sel:DWORD dst_unused:UNUSED_PAD src0_sel:WORD_1
	v_cvt_f32_f16_e32 v198, v199
	v_cvt_f32_f16_sdwa v209, v200 dst_sel:DWORD dst_unused:UNUSED_PAD src0_sel:WORD_1
	v_cvt_f32_f16_e32 v208, v200
	v_cvt_f32_f16_sdwa v207, v201 dst_sel:DWORD dst_unused:UNUSED_PAD src0_sel:WORD_1
	v_cvt_f32_f16_e32 v210, v201
	v_cvt_f32_i32_e32 v177, v115
	v_cvt_f32_i32_e32 v176, v114
	v_cvt_f32_i32_e32 v179, v117
	v_cvt_f32_i32_e32 v178, v116
	v_lshl_add_u64 v[204:205], v[146:147], 0, v[202:203]
	v_sub_f32_e32 v198, v198, v154
	v_sub_f32_e32 v199, v206, v154
	v_sub_f32_e32 v200, v185, v154
	v_sub_f32_e32 v201, v155, v154
	v_sub_f32_e32 v206, v210, v154
	v_sub_f32_e32 v207, v207, v154
	v_sub_f32_e32 v208, v208, v154
	v_sub_f32_e32 v209, v209, v154
	global_load_dwordx4 v[114:117], v[204:205], off
	v_cvt_f32_i32_e32 v48, v48
	v_cvt_f32_i32_e32 v43, v43
	v_cvt_f32_i32_e32 v42, v42
	v_cvt_f32_i32_e32 v45, v45
	v_cvt_f32_i32_e32 v44, v44
	v_cvt_f32_i32_e32 v39, v39
	v_cvt_f32_i32_e32 v38, v38
	v_cvt_f32_i32_e32 v41, v41
	v_cvt_f32_i32_e32 v40, v40
	v_cvt_f32_i32_e32 v31, v31
	v_cvt_f32_i32_e32 v30, v30
	v_cvt_f32_i32_e32 v33, v33
	v_cvt_f32_i32_e32 v32, v32
	v_cvt_f32_i32_e32 v23, v23
	v_cvt_f32_i32_e32 v22, v22
	v_cvt_f32_i32_e32 v25, v25
	v_cvt_f32_i32_e32 v24, v24
	v_cvt_f32_i32_e32 v19, v19
	v_cvt_f32_i32_e32 v18, v18
	v_cvt_f32_i32_e32 v21, v21
	v_cvt_f32_i32_e32 v20, v20
	v_cvt_f32_i32_e32 v15, v15
	v_cvt_f32_i32_e32 v14, v14
	v_cvt_f32_i32_e32 v17, v17
	v_cvt_f32_i32_e32 v16, v16
	v_cvt_f32_i32_e32 v11, v11
	v_cvt_f32_i32_e32 v10, v10
	v_cvt_f32_i32_e32 v13, v13
	v_cvt_f32_i32_e32 v12, v12
	v_cvt_f32_i32_e32 v7, v7
	v_cvt_f32_i32_e32 v6, v6
	v_cvt_f32_i32_e32 v9, v9
	v_cvt_f32_i32_e32 v8, v8
	v_cvt_f32_i32_e32 v3, v3
	v_cvt_f32_i32_e32 v2, v2
	v_cvt_f32_i32_e32 v5, v5
	v_cvt_f32_i32_e32 v4, v4
	v_readlane_b32 s34, v251, 3
	s_and_b64 vcc, exec, s[4:5]
	s_mov_b64 s[4:5], -1
	v_readlane_b32 s35, v251, 4
	s_waitcnt vmcnt(4)
	v_pk_mul_f32 v[154:155], v[190:191], v[162:163] op_sel_hi:[0,1]
	v_pk_mul_f32 v[160:161], v[190:191], v[160:161] op_sel_hi:[0,1]
	s_waitcnt vmcnt(3)
	v_pk_mul_f32 v[162:163], v[190:191], v[166:167] op_sel_hi:[0,1]
	v_pk_mul_f32 v[164:165], v[190:191], v[164:165] op_sel_hi:[0,1]
	s_waitcnt vmcnt(2)
	v_pk_mul_f32 v[166:167], v[170:171], s[90:91] op_sel_hi:[1,0]
	v_pk_mul_f32 v[168:169], v[168:169], s[90:91] op_sel_hi:[1,0]
	s_waitcnt vmcnt(1)
	v_pk_mul_f32 v[170:171], v[174:175], s[90:91] op_sel_hi:[1,0]
	v_pk_mul_f32 v[172:173], v[172:173], s[90:91] op_sel_hi:[1,0]
	v_pk_fma_f32 v[160:161], v[200:201], v[160:161], v[168:169]
	v_pk_fma_f32 v[154:155], v[198:199], v[154:155], v[166:167]
	v_pk_fma_f32 v[164:165], v[208:209], v[164:165], v[172:173]
	v_pk_fma_f32 v[162:163], v[206:207], v[162:163], v[170:171]
	v_pk_fma_f32 v[120:121], v[186:187], v[120:121], v[154:155] op_sel_hi:[0,1,1]
	v_pk_fma_f32 v[118:119], v[186:187], v[118:119], v[160:161] op_sel_hi:[0,1,1]
	v_pk_fma_f32 v[154:155], v[186:187], v[178:179], v[162:163] op_sel_hi:[0,1,1]
	v_pk_fma_f32 v[160:161], v[186:187], v[176:177], v[164:165] op_sel_hi:[0,1,1]
	v_cvt_pk_f16_f32 v118, v118, v119
	v_cvt_pk_f16_f32 v119, v120, v121
	v_cvt_pk_f16_f32 v120, v160, v161
	v_cvt_pk_f16_f32 v121, v154, v155
	global_store_dwordx4 v[180:181], v[118:121], off offset:256
	s_nop 0
	v_mul_f32_e32 v178, 0x3fb504f3, v129
	v_cvt_f32_i32_e32 v155, v107
	v_cvt_f32_i32_e32 v154, v106
	v_cvt_f32_i32_e32 v173, v109
	s_waitcnt vmcnt(1)
	v_cvt_f32_f16_sdwa v129, v114 dst_sel:DWORD dst_unused:UNUSED_PAD src0_sel:WORD_1
	v_cvt_f32_f16_e32 v177, v114
	v_cvt_f32_f16_sdwa v179, v115 dst_sel:DWORD dst_unused:UNUSED_PAD src0_sel:WORD_1
	v_cvt_f32_f16_e32 v114, v115
	v_cvt_f32_f16_sdwa v185, v116 dst_sel:DWORD dst_unused:UNUSED_PAD src0_sel:WORD_1
	v_cvt_f32_f16_e32 v186, v116
	v_cvt_f32_f16_sdwa v181, v117 dst_sel:DWORD dst_unused:UNUSED_PAD src0_sel:WORD_1
	v_cvt_f32_f16_e32 v180, v117
	v_cvt_f32_i32_e32 v172, v108
	v_sub_f32_e32 v114, v114, v128
	v_sub_f32_e32 v115, v179, v128
	v_sub_f32_e32 v116, v177, v128
	v_sub_f32_e32 v117, v129, v128
	v_sub_f32_e32 v180, v180, v128
	v_sub_f32_e32 v181, v181, v128
	v_sub_f32_e32 v198, v186, v128
	v_sub_f32_e32 v199, v185, v128
	global_load_dwordx4 v[106:109], v[204:205], off offset:256
	v_mul_f32_e32 v176, v151, v189
	v_lshl_add_u64 v[174:175], s[10:11], 0, v[202:203]
	v_lshl_add_u64 v[174:175], v[174:175], 0, v[144:145]
	s_waitcnt vmcnt(1)
	v_pk_mul_f32 v[120:121], v[178:179], v[248:249] op_sel_hi:[0,1]
	v_pk_mul_f32 v[118:119], v[178:179], v[246:247] op_sel_hi:[0,1]
	s_waitcnt vmcnt(1)
	v_pk_mul_f32 v[162:163], v[178:179], v[244:245] op_sel_hi:[0,1]
	v_pk_mul_f32 v[160:161], v[178:179], v[242:243] op_sel_hi:[0,1]
	s_waitcnt vmcnt(1)
	v_pk_mul_f32 v[166:167], v[240:241], s[90:91] op_sel_hi:[1,0]
	v_pk_mul_f32 v[164:165], v[238:239], s[90:91] op_sel_hi:[1,0]
	s_waitcnt vmcnt(1)
; __device__ __forceinline__ u32x4 pk8h(const f32x4 a, const f32x4 b) { u32x4 w; w.x = pkh(a[0], a[1]); w.y = pkh(a[2], a[3]); w.z = pkh(b[0], b[1]); w.w = pkh(b[2], b[3]); return w; }
; __device__ __forceinline__ f32x4 h4lo(const u32x4 w) { return (f32x4){hlo(w.x), hhi(w.x), hlo(w.y), hhi(w.y)}; }
; __device__ __forceinline__ f32x4 h4hi(const u32x4 w) { return (f32x4){hlo(w.z), hhi(w.z), hlo(w.w), hhi(w.w)}; }
;     __device__ __forceinline__ void operator()(const i32x4 (&acc)[2][2][4][2], const Unit& u, int wr, int wc, int fr, int fq) const {
;     ...
;             for (int m = 0; m < 4; ++m) { const int row = row0 + ai * HALF + m * 16; const bf16_t* yp = X + (size_t)row * 4096 + col0; y[m][0] = *(const u32x4*)yp; y[m][1] = *(const u32x4*)(yp + HALF);
;                 mean[m] = stats[2 * row]; rstd[m] = stats[2 * row + 1]; f[m] = rowinv[row] * wdq; }
; #pragma unroll
;             for (int m = 0; m < 4; ++m) { bf16_t* rowp = X + (size_t)(row0 + ai * HALF + m * 16) * 4096 + col0;
; #pragma unroll
;                 for (int bj = 0; bj < 2; ++bj) { const int c = col0 + bj * HALF; const float ra = rstd[m] * alpha;
;                     const f32x4 g0 = *(const f32x4*)(g + c) * ra, g1 = *(const f32x4*)(g + c + 4) * ra, b0 = *(const f32x4*)(b + c) * alpha, b1 = *(const f32x4*)(b + c + 4) * alpha;
;                     const i32x4 a0 = acc[ai][bj][m][0], a1 = acc[ai][bj][m][1];
;                     f32x4 q0, q1; q0.x = (float)a0.x; q0.y = (float)a0.y; q0.z = (float)a0.z; q0.w = (float)a0.w; q1.x = (float)a1.x; q1.y = (float)a1.y; q1.z = (float)a1.z; q1.w = (float)a1.w;
;                     *(u32x4*)(rowp + bj * HALF) = pk8h((h4lo(y[m][bj]) - mean[m]) * g0 + b0 + q0 * f[m], (h4hi(y[m][bj]) - mean[m]) * g1 + b1 + q1 * f[m]); } }
	v_pk_mul_f32 v[170:171], v[236:237], s[90:91] op_sel_hi:[1,0]
	v_pk_mul_f32 v[168:169], v[234:235], s[90:91] op_sel_hi:[1,0]
	v_pk_fma_f32 v[116:117], v[116:117], v[118:119], v[164:165]
	v_pk_fma_f32 v[114:115], v[114:115], v[120:121], v[166:167]
	v_pk_fma_f32 v[118:119], v[198:199], v[160:161], v[168:169]
	v_pk_fma_f32 v[120:121], v[180:181], v[162:163], v[170:171]
	v_pk_fma_f32 v[112:113], v[176:177], v[112:113], v[114:115] op_sel_hi:[0,1,1]
	v_pk_fma_f32 v[110:111], v[176:177], v[110:111], v[116:117] op_sel_hi:[0,1,1]
	v_pk_fma_f32 v[114:115], v[176:177], v[172:173], v[120:121] op_sel_hi:[0,1,1]
	v_pk_fma_f32 v[116:117], v[176:177], v[154:155], v[118:119] op_sel_hi:[0,1,1]
	v_cvt_pk_f16_f32 v110, v110, v111
	v_cvt_pk_f16_f32 v111, v112, v113
	v_cvt_pk_f16_f32 v112, v116, v117
	v_cvt_pk_f16_f32 v113, v114, v115
	global_store_dwordx4 v[174:175], v[110:113], off
	global_load_dwordx4 v[110:113], v[142:143], off offset:512
	s_nop 0
	global_load_dwordx4 v[114:117], v[142:143], off offset:528
	global_load_dwordx4 v[118:121], v[140:141], off offset:512
	global_load_dwordx4 v[160:163], v[140:141], off offset:528
	v_cvt_f32_i32_e32 v155, v99
	v_cvt_f32_i32_e32 v154, v98
	v_cvt_f32_i32_e32 v165, v101
	s_waitcnt vmcnt(5)
	v_cvt_f32_f16_sdwa v129, v106 dst_sel:DWORD dst_unused:UNUSED_PAD src0_sel:WORD_1
	v_cvt_f32_f16_e32 v168, v106
	v_cvt_f32_f16_sdwa v169, v107 dst_sel:DWORD dst_unused:UNUSED_PAD src0_sel:WORD_1
	v_cvt_f32_f16_e32 v106, v107
	v_cvt_f32_f16_sdwa v171, v108 dst_sel:DWORD dst_unused:UNUSED_PAD src0_sel:WORD_1
	v_cvt_f32_f16_e32 v170, v108
	v_cvt_f32_f16_sdwa v172, v109 dst_sel:DWORD dst_unused:UNUSED_PAD src0_sel:WORD_1
	v_cvt_f32_f16_e32 v173, v109
	v_cvt_f32_i32_e32 v164, v100
	v_lshl_add_u64 v[166:167], v[146:147], 0, v[152:153]
	v_sub_f32_e32 v106, v106, v128
	v_sub_f32_e32 v107, v169, v128
	v_sub_f32_e32 v108, v168, v128
	v_sub_f32_e32 v109, v129, v128
	v_sub_f32_e32 v168, v173, v128
	v_sub_f32_e32 v169, v172, v128
	v_sub_f32_e32 v170, v170, v128
	v_sub_f32_e32 v171, v171, v128
	global_load_dwordx4 v[98:101], v[166:167], off
	s_waitcnt vmcnt(4)
	v_pk_mul_f32 v[112:113], v[178:179], v[112:113] op_sel_hi:[0,1]
	v_pk_mul_f32 v[110:111], v[178:179], v[110:111] op_sel_hi:[0,1]
	s_waitcnt vmcnt(3)
	v_pk_mul_f32 v[116:117], v[178:179], v[116:117] op_sel_hi:[0,1]
	v_pk_mul_f32 v[114:115], v[178:179], v[114:115] op_sel_hi:[0,1]
	s_waitcnt vmcnt(2)
	v_pk_mul_f32 v[120:121], v[120:121], s[90:91] op_sel_hi:[1,0]
	v_pk_mul_f32 v[118:119], v[118:119], s[90:91] op_sel_hi:[1,0]
	s_waitcnt vmcnt(1)
	v_pk_mul_f32 v[128:129], v[162:163], s[90:91] op_sel_hi:[1,0]
	v_pk_mul_f32 v[160:161], v[160:161], s[90:91] op_sel_hi:[1,0]
	v_pk_fma_f32 v[108:109], v[108:109], v[110:111], v[118:119]
	v_pk_fma_f32 v[106:107], v[106:107], v[112:113], v[120:121]
	v_pk_fma_f32 v[110:111], v[170:171], v[114:115], v[160:161]
	v_pk_fma_f32 v[112:113], v[168:169], v[116:117], v[128:129]
	v_pk_fma_f32 v[104:105], v[176:177], v[104:105], v[106:107] op_sel_hi:[0,1,1]
	v_pk_fma_f32 v[102:103], v[176:177], v[102:103], v[108:109] op_sel_hi:[0,1,1]
	v_pk_fma_f32 v[106:107], v[176:177], v[164:165], v[112:113] op_sel_hi:[0,1,1]
	v_pk_fma_f32 v[108:109], v[176:177], v[154:155], v[110:111] op_sel_hi:[0,1,1]
	v_cvt_pk_f16_f32 v102, v102, v103
	v_cvt_pk_f16_f32 v103, v104, v105
	v_cvt_pk_f16_f32 v104, v108, v109
	v_cvt_pk_f16_f32 v105, v106, v107
	global_store_dwordx4 v[174:175], v[102:105], off offset:256
	s_nop 0
	v_lshl_add_u64 v[128:129], s[10:11], 0, v[152:153]
	v_mul_f32_e32 v154, 0x3fb504f3, v125
	v_cvt_f32_i32_e32 v119, v91
	s_waitcnt vmcnt(1)
	v_cvt_f32_f16_sdwa v125, v98 dst_sel:DWORD dst_unused:UNUSED_PAD src0_sel:WORD_1
	v_cvt_f32_f16_e32 v153, v98
	v_cvt_f32_f16_sdwa v155, v99 dst_sel:DWORD dst_unused:UNUSED_PAD src0_sel:WORD_1
	v_cvt_f32_f16_e32 v98, v99
	v_cvt_f32_f16_sdwa v163, v100 dst_sel:DWORD dst_unused:UNUSED_PAD src0_sel:WORD_1
	v_cvt_f32_f16_e32 v162, v100
	v_cvt_f32_f16_sdwa v161, v101 dst_sel:DWORD dst_unused:UNUSED_PAD src0_sel:WORD_1
	v_cvt_f32_f16_e32 v160, v101
	v_cvt_f32_i32_e32 v118, v90
	v_cvt_f32_i32_e32 v121, v93
	v_cvt_f32_i32_e32 v120, v92
	v_sub_f32_e32 v98, v98, v124
	v_sub_f32_e32 v99, v155, v124
	v_sub_f32_e32 v100, v153, v124
	v_sub_f32_e32 v101, v125, v124
	v_sub_f32_e32 v160, v160, v124
	v_sub_f32_e32 v161, v161, v124
	v_sub_f32_e32 v162, v162, v124
	v_sub_f32_e32 v163, v163, v124
	global_load_dwordx4 v[90:93], v[166:167], off offset:256
	v_mul_f32_e32 v152, v151, v192
	v_lshl_add_u64 v[128:129], v[128:129], 0, v[144:145]
	s_waitcnt vmcnt(1)
	v_pk_mul_f32 v[104:105], v[154:155], v[248:249] op_sel_hi:[0,1]
	v_pk_mul_f32 v[102:103], v[154:155], v[246:247] op_sel_hi:[0,1]
	s_waitcnt vmcnt(1)
	v_pk_mul_f32 v[108:109], v[154:155], v[244:245] op_sel_hi:[0,1]
	v_pk_mul_f32 v[106:107], v[154:155], v[242:243] op_sel_hi:[0,1]
	s_waitcnt vmcnt(1)
	v_pk_mul_f32 v[112:113], v[240:241], s[90:91] op_sel_hi:[1,0]
	v_pk_mul_f32 v[110:111], v[238:239], s[90:91] op_sel_hi:[1,0]
	s_waitcnt vmcnt(1)
	v_pk_mul_f32 v[116:117], v[236:237], s[90:91] op_sel_hi:[1,0]
	v_pk_mul_f32 v[114:115], v[234:235], s[90:91] op_sel_hi:[1,0]
	v_pk_fma_f32 v[100:101], v[100:101], v[102:103], v[110:111]
	v_pk_fma_f32 v[98:99], v[98:99], v[104:105], v[112:113]
	v_pk_fma_f32 v[102:103], v[162:163], v[106:107], v[114:115]
	v_pk_fma_f32 v[104:105], v[160:161], v[108:109], v[116:117]
	v_pk_fma_f32 v[96:97], v[152:153], v[96:97], v[98:99] op_sel_hi:[0,1,1]
	v_pk_fma_f32 v[94:95], v[152:153], v[94:95], v[100:101] op_sel_hi:[0,1,1]
	v_pk_fma_f32 v[98:99], v[152:153], v[120:121], v[104:105] op_sel_hi:[0,1,1]
	v_pk_fma_f32 v[100:101], v[152:153], v[118:119], v[102:103] op_sel_hi:[0,1,1]
	v_cvt_pk_f16_f32 v94, v94, v95
	v_cvt_pk_f16_f32 v95, v96, v97
	v_cvt_pk_f16_f32 v96, v100, v101
	v_cvt_pk_f16_f32 v97, v98, v99
	global_store_dwordx4 v[128:129], v[94:97], off
	global_load_dwordx4 v[94:97], v[142:143], off offset:512
	s_nop 0
	global_load_dwordx4 v[98:101], v[142:143], off offset:528
	global_load_dwordx4 v[102:105], v[140:141], off offset:512
	global_load_dwordx4 v[106:109], v[140:141], off offset:528
	v_lshlrev_b64 v[114:115], 13, v[126:127]
	v_cvt_f32_i32_e32 v111, v83
	v_cvt_f32_i32_e32 v110, v82
	v_cvt_f32_i32_e32 v113, v85
	s_waitcnt vmcnt(5)
; __device__ __forceinline__ u32x4 pk8h(const f32x4 a, const f32x4 b) { u32x4 w; w.x = pkh(a[0], a[1]); w.y = pkh(a[2], a[3]); w.z = pkh(b[0], b[1]); w.w = pkh(b[2], b[3]); return w; }
; __device__ __forceinline__ f32x4 h4lo(const u32x4 w) { return (f32x4){hlo(w.x), hhi(w.x), hlo(w.y), hhi(w.y)}; }
; __device__ __forceinline__ f32x4 h4hi(const u32x4 w) { return (f32x4){hlo(w.z), hhi(w.z), hlo(w.w), hhi(w.w)}; }
;     __device__ __forceinline__ void operator()(const i32x4 (&acc)[2][2][4][2], const Unit& u, int wr, int wc, int fr, int fq) const {
;     ...
;             for (int m = 0; m < 4; ++m) { const int row = row0 + ai * HALF + m * 16; const bf16_t* yp = X + (size_t)row * 4096 + col0; y[m][0] = *(const u32x4*)yp; y[m][1] = *(const u32x4*)(yp + HALF);
;                 mean[m] = stats[2 * row]; rstd[m] = stats[2 * row + 1]; f[m] = rowinv[row] * wdq; }
; #pragma unroll
;             for (int m = 0; m < 4; ++m) { bf16_t* rowp = X + (size_t)(row0 + ai * HALF + m * 16) * 4096 + col0;
; #pragma unroll
;                 for (int bj = 0; bj < 2; ++bj) { const int c = col0 + bj * HALF; const float ra = rstd[m] * alpha;
;                     const f32x4 g0 = *(const f32x4*)(g + c) * ra, g1 = *(const f32x4*)(g + c + 4) * ra, b0 = *(const f32x4*)(b + c) * alpha, b1 = *(const f32x4*)(b + c + 4) * alpha;
;                     const i32x4 a0 = acc[ai][bj][m][0], a1 = acc[ai][bj][m][1];
;                     f32x4 q0, q1; q0.x = (float)a0.x; q0.y = (float)a0.y; q0.z = (float)a0.z; q0.w = (float)a0.w; q1.x = (float)a1.x; q1.y = (float)a1.y; q1.z = (float)a1.z; q1.w = (float)a1.w;
;                     *(u32x4*)(rowp + bj * HALF) = pk8h((h4lo(y[m][bj]) - mean[m]) * g0 + b0 + q0 * f[m], (h4hi(y[m][bj]) - mean[m]) * g1 + b1 + q1 * f[m]); } }
	v_cvt_f32_f16_sdwa v118, v90 dst_sel:DWORD dst_unused:UNUSED_PAD src0_sel:WORD_1
	v_cvt_f32_f16_e32 v119, v90
	v_cvt_f32_f16_sdwa v120, v91 dst_sel:DWORD dst_unused:UNUSED_PAD src0_sel:WORD_1
	v_cvt_f32_f16_e32 v90, v91
	v_cvt_f32_f16_sdwa v121, v92 dst_sel:DWORD dst_unused:UNUSED_PAD src0_sel:WORD_1
	v_cvt_f32_f16_e32 v125, v92
	v_cvt_f32_f16_sdwa v126, v93 dst_sel:DWORD dst_unused:UNUSED_PAD src0_sel:WORD_1
	v_cvt_f32_f16_e32 v127, v93
	v_cvt_f32_i32_e32 v112, v84
	v_lshl_add_u64 v[116:117], v[146:147], 0, v[114:115]
	v_sub_f32_e32 v90, v90, v124
	v_sub_f32_e32 v91, v120, v124
	v_sub_f32_e32 v92, v119, v124
	v_sub_f32_e32 v93, v118, v124
	v_sub_f32_e32 v118, v127, v124
	v_sub_f32_e32 v119, v126, v124
	v_sub_f32_e32 v120, v125, v124
	v_sub_f32_e32 v121, v121, v124
	global_load_dwordx4 v[82:85], v[116:117], off
	s_waitcnt vmcnt(4)
	v_pk_mul_f32 v[96:97], v[154:155], v[96:97] op_sel_hi:[0,1]
	v_pk_mul_f32 v[94:95], v[154:155], v[94:95] op_sel_hi:[0,1]
	s_waitcnt vmcnt(3)
	v_pk_mul_f32 v[100:101], v[154:155], v[100:101] op_sel_hi:[0,1]
	v_pk_mul_f32 v[98:99], v[154:155], v[98:99] op_sel_hi:[0,1]
	s_waitcnt vmcnt(2)
	v_pk_mul_f32 v[104:105], v[104:105], s[90:91] op_sel_hi:[1,0]
	v_pk_mul_f32 v[102:103], v[102:103], s[90:91] op_sel_hi:[1,0]
	s_waitcnt vmcnt(1)
	v_pk_mul_f32 v[108:109], v[108:109], s[90:91] op_sel_hi:[1,0]
	v_pk_mul_f32 v[106:107], v[106:107], s[90:91] op_sel_hi:[1,0]
	v_pk_fma_f32 v[92:93], v[92:93], v[94:95], v[102:103]
	v_pk_fma_f32 v[90:91], v[90:91], v[96:97], v[104:105]
	v_pk_fma_f32 v[94:95], v[120:121], v[98:99], v[106:107]
	v_pk_fma_f32 v[96:97], v[118:119], v[100:101], v[108:109]
	v_pk_fma_f32 v[88:89], v[152:153], v[88:89], v[90:91] op_sel_hi:[0,1,1]
	v_pk_fma_f32 v[86:87], v[152:153], v[86:87], v[92:93] op_sel_hi:[0,1,1]
	v_pk_fma_f32 v[90:91], v[152:153], v[112:113], v[96:97] op_sel_hi:[0,1,1]
	v_pk_fma_f32 v[92:93], v[152:153], v[110:111], v[94:95] op_sel_hi:[0,1,1]
	v_cvt_pk_f16_f32 v86, v86, v87
	v_cvt_pk_f16_f32 v87, v88, v89
	v_cvt_pk_f16_f32 v88, v92, v93
	v_cvt_pk_f16_f32 v89, v90, v91
	global_store_dwordx4 v[128:129], v[86:89], off offset:256
	s_nop 0
	v_cvt_f32_i32_e32 v103, v75
	v_cvt_f32_i32_e32 v102, v74
	v_cvt_f32_i32_e32 v105, v77
	v_cvt_f32_i32_e32 v104, v76
	v_lshl_add_u64 v[106:107], s[10:11], 0, v[114:115]
	global_load_dwordx4 v[74:77], v[116:117], off offset:256
	s_waitcnt vmcnt(2)
	v_cvt_f32_f16_sdwa v109, v82 dst_sel:DWORD dst_unused:UNUSED_PAD src0_sel:WORD_1
	v_cvt_f32_f16_e32 v111, v82
	v_cvt_f32_f16_sdwa v112, v83 dst_sel:DWORD dst_unused:UNUSED_PAD src0_sel:WORD_1
	v_cvt_f32_f16_e32 v82, v83
	v_cvt_f32_f16_sdwa v115, v84 dst_sel:DWORD dst_unused:UNUSED_PAD src0_sel:WORD_1
	v_cvt_f32_f16_e32 v114, v84
	v_cvt_f32_f16_sdwa v113, v85 dst_sel:DWORD dst_unused:UNUSED_PAD src0_sel:WORD_1
	v_cvt_f32_f16_e32 v116, v85
	v_mul_f32_e32 v110, 0x3fb504f3, v123
	v_sub_f32_e32 v82, v82, v122
	v_sub_f32_e32 v83, v112, v122
	v_sub_f32_e32 v84, v111, v122
	v_sub_f32_e32 v85, v109, v122
	v_sub_f32_e32 v112, v116, v122
	v_sub_f32_e32 v113, v113, v122
	v_sub_f32_e32 v114, v114, v122
	v_sub_f32_e32 v115, v115, v122
	v_mul_f32_e32 v108, v151, v159
	v_lshl_add_u64 v[106:107], v[106:107], 0, v[144:145]
	v_cvt_f32_i32_e32 v116, v58
	v_cvt_f32_i32_e32 v120, v60
	v_add_u32_e32 v58, 0x90, v150
	v_add_u32_e32 v60, 0xb0, v150
	v_cvt_f32_i32_e32 v118, v64
	v_cvt_f32_i32_e32 v117, v59
	v_cvt_f32_i32_e32 v121, v61
	v_ashrrev_i32_e32 v59, 31, v58
	v_ashrrev_i32_e32 v61, 31, v60
	v_cvt_f32_i32_e32 v119, v65
	s_waitcnt vmcnt(1)
	v_pk_mul_f32 v[88:89], v[110:111], v[248:249] op_sel_hi:[0,1]
	v_pk_mul_f32 v[86:87], v[110:111], v[246:247] op_sel_hi:[0,1]
	s_waitcnt vmcnt(1)
	v_pk_mul_f32 v[92:93], v[110:111], v[244:245] op_sel_hi:[0,1]
	v_pk_mul_f32 v[90:91], v[110:111], v[242:243] op_sel_hi:[0,1]
	s_waitcnt vmcnt(1)
	v_pk_mul_f32 v[96:97], v[240:241], s[90:91] op_sel_hi:[1,0]
	v_pk_mul_f32 v[94:95], v[238:239], s[90:91] op_sel_hi:[1,0]
	s_waitcnt vmcnt(1)
	v_pk_mul_f32 v[100:101], v[236:237], s[90:91] op_sel_hi:[1,0]
	v_pk_mul_f32 v[98:99], v[234:235], s[90:91] op_sel_hi:[1,0]
	v_pk_fma_f32 v[84:85], v[84:85], v[86:87], v[94:95]
	v_pk_fma_f32 v[82:83], v[82:83], v[88:89], v[96:97]
	v_pk_fma_f32 v[86:87], v[114:115], v[90:91], v[98:99]
	v_pk_fma_f32 v[88:89], v[112:113], v[92:93], v[100:101]
	v_pk_fma_f32 v[80:81], v[108:109], v[80:81], v[82:83] op_sel_hi:[0,1,1]
	v_pk_fma_f32 v[78:79], v[108:109], v[78:79], v[84:85] op_sel_hi:[0,1,1]
	v_pk_fma_f32 v[82:83], v[108:109], v[104:105], v[88:89] op_sel_hi:[0,1,1]
	v_pk_fma_f32 v[84:85], v[108:109], v[102:103], v[86:87] op_sel_hi:[0,1,1]
	v_cvt_pk_f16_f32 v78, v78, v79
	v_cvt_pk_f16_f32 v79, v80, v81
	v_cvt_pk_f16_f32 v80, v84, v85
	v_cvt_pk_f16_f32 v81, v82, v83
	global_store_dwordx4 v[106:107], v[78:81], off
	global_load_dwordx4 v[78:81], v[142:143], off offset:512
	s_nop 0
	global_load_dwordx4 v[82:85], v[142:143], off offset:528
	global_load_dwordx4 v[86:89], v[140:141], off offset:512
	global_load_dwordx4 v[90:93], v[140:141], off offset:528
	s_waitcnt vmcnt(5)
	v_cvt_f32_f16_sdwa v95, v74 dst_sel:DWORD dst_unused:UNUSED_PAD src0_sel:WORD_1
	v_cvt_f32_f16_e32 v98, v74
	v_cvt_f32_f16_sdwa v99, v75 dst_sel:DWORD dst_unused:UNUSED_PAD src0_sel:WORD_1
	v_cvt_f32_f16_e32 v74, v75
	v_cvt_f32_f16_sdwa v101, v76 dst_sel:DWORD dst_unused:UNUSED_PAD src0_sel:WORD_1
	v_cvt_f32_f16_e32 v100, v76
	v_cvt_f32_f16_sdwa v102, v77 dst_sel:DWORD dst_unused:UNUSED_PAD src0_sel:WORD_1
	v_cvt_f32_f16_e32 v103, v77
	v_sub_f32_e32 v74, v74, v122
	v_sub_f32_e32 v75, v99, v122
	v_sub_f32_e32 v76, v98, v122
	v_sub_f32_e32 v77, v95, v122
	v_sub_f32_e32 v98, v103, v122
	v_sub_f32_e32 v99, v102, v122
	v_sub_f32_e32 v100, v100, v122
	v_sub_f32_e32 v101, v101, v122
	v_add_u32_e32 v94, 0x80, v150
	v_lshlrev_b32_e32 v96, 1, v94
	v_ashrrev_i32_e32 v95, 31, v94
	v_ashrrev_i32_e32 v97, 31, v96
	v_lshl_add_u64 v[96:97], v[96:97], 2, s[36:37]
	v_cvt_f32_i32_e32 v114, v62
	v_lshlrev_b32_e32 v62, 1, v58
	v_cvt_f32_i32_e32 v115, v63
	v_ashrrev_i32_e32 v63, 31, v62
	s_waitcnt vmcnt(3)
; __device__ __forceinline__ u32x4 pk8h(const f32x4 a, const f32x4 b) { u32x4 w; w.x = pkh(a[0], a[1]); w.y = pkh(a[2], a[3]); w.z = pkh(b[0], b[1]); w.w = pkh(b[2], b[3]); return w; }
; __device__ __forceinline__ f32x4 h4lo(const u32x4 w) { return (f32x4){hlo(w.x), hhi(w.x), hlo(w.y), hhi(w.y)}; }
; __device__ __forceinline__ f32x4 h4hi(const u32x4 w) { return (f32x4){hlo(w.z), hhi(w.z), hlo(w.w), hhi(w.w)}; }
;     __device__ __forceinline__ void operator()(const i32x4 (&acc)[2][2][4][2], const Unit& u, int wr, int wc, int fr, int fq) const {
;     ...
;             u32x4 y[4][2]; float mean[4], rstd[4], f[4];
; #pragma unroll
;             for (int m = 0; m < 4; ++m) { const int row = row0 + ai * HALF + m * 16; const bf16_t* yp = X + (size_t)row * 4096 + col0; y[m][0] = *(const u32x4*)yp; y[m][1] = *(const u32x4*)(yp + HALF);
;                 mean[m] = stats[2 * row]; rstd[m] = stats[2 * row + 1]; f[m] = rowinv[row] * wdq; }
; #pragma unroll
;             for (int m = 0; m < 4; ++m) { bf16_t* rowp = X + (size_t)(row0 + ai * HALF + m * 16) * 4096 + col0;
; #pragma unroll
;                 for (int bj = 0; bj < 2; ++bj) { const int c = col0 + bj * HALF; const float ra = rstd[m] * alpha;
;                     const f32x4 g0 = *(const f32x4*)(g + c) * ra, g1 = *(const f32x4*)(g + c + 4) * ra, b0 = *(const f32x4*)(b + c) * alpha, b1 = *(const f32x4*)(b + c + 4) * alpha;
;                     const i32x4 a0 = acc[ai][bj][m][0], a1 = acc[ai][bj][m][1];
;                     f32x4 q0, q1; q0.x = (float)a0.x; q0.y = (float)a0.y; q0.z = (float)a0.z; q0.w = (float)a0.w; q1.x = (float)a1.x; q1.y = (float)a1.y; q1.z = (float)a1.z; q1.w = (float)a1.w;
;                     *(u32x4*)(rowp + bj * HALF) = pk8h((h4lo(y[m][bj]) - mean[m]) * g0 + b0 + q0 * f[m], (h4hi(y[m][bj]) - mean[m]) * g1 + b1 + q1 * f[m]); } }
	v_pk_mul_f32 v[80:81], v[110:111], v[80:81] op_sel_hi:[0,1]
	v_pk_mul_f32 v[78:79], v[110:111], v[78:79] op_sel_hi:[0,1]
	s_waitcnt vmcnt(2)
	v_pk_mul_f32 v[84:85], v[110:111], v[84:85] op_sel_hi:[0,1]
	v_pk_mul_f32 v[82:83], v[110:111], v[82:83] op_sel_hi:[0,1]
	s_waitcnt vmcnt(1)
	v_pk_mul_f32 v[88:89], v[88:89], s[90:91] op_sel_hi:[1,0]
	v_pk_mul_f32 v[86:87], v[86:87], s[90:91] op_sel_hi:[1,0]
	s_waitcnt vmcnt(0)
	v_pk_mul_f32 v[92:93], v[92:93], s[90:91] op_sel_hi:[1,0]
	v_pk_mul_f32 v[90:91], v[90:91], s[90:91] op_sel_hi:[1,0]
	v_pk_fma_f32 v[76:77], v[76:77], v[78:79], v[86:87]
	v_pk_fma_f32 v[74:75], v[74:75], v[80:81], v[88:89]
	v_pk_fma_f32 v[78:79], v[100:101], v[82:83], v[90:91]
	v_pk_fma_f32 v[80:81], v[98:99], v[84:85], v[92:93]
	v_pk_fma_f32 v[72:73], v[108:109], v[72:73], v[74:75] op_sel_hi:[0,1,1]
	v_pk_fma_f32 v[70:71], v[108:109], v[70:71], v[76:77] op_sel_hi:[0,1,1]
	v_pk_fma_f32 v[74:75], v[108:109], v[68:69], v[80:81] op_sel_hi:[0,1,1]
	v_pk_fma_f32 v[68:69], v[108:109], v[66:67], v[78:79] op_sel_hi:[0,1,1]
	v_cvt_pk_f16_f32 v66, v70, v71
	v_cvt_pk_f16_f32 v67, v72, v73
	v_cvt_pk_f16_f32 v68, v68, v69
	v_cvt_pk_f16_f32 v69, v74, v75
	global_store_dwordx4 v[106:107], v[66:69], off offset:256
	v_lshlrev_b64 v[86:87], 13, v[94:95]
	v_lshl_add_u64 v[88:89], v[146:147], 0, v[86:87]
	global_load_dwordx2 v[100:101], v[96:97], off
	global_load_dword v107, v[148:149], off offset:512
	global_load_dwordx4 v[82:85], v[88:89], off
	v_add_u32_e32 v106, 0xa0, v150
	v_lshlrev_b32_e32 v64, 1, v106
	v_lshlrev_b32_e32 v90, 1, v60
	v_lshlrev_b64 v[110:111], 13, v[58:59]
	v_ashrrev_i32_e32 v65, 31, v64
	v_lshlrev_b64 v[98:99], 13, v[60:61]
	v_ashrrev_i32_e32 v91, 31, v90
	v_lshl_add_u64 v[92:93], v[146:147], 0, v[110:111]
	v_lshl_add_u64 v[96:97], v[62:63], 2, s[36:37]
	v_lshl_add_u64 v[58:59], v[64:65], 2, s[36:37]
	v_lshl_add_u64 v[94:95], v[146:147], 0, v[98:99]
	v_lshl_add_u64 v[104:105], v[90:91], 2, s[36:37]
	v_lshl_add_u64 v[60:61], s[10:11], 0, v[86:87]
	v_lshl_add_u64 v[112:113], v[60:61], 0, v[144:145]
	global_load_dwordx4 v[86:89], v[88:89], off offset:256
	s_nop 0
	global_load_dwordx4 v[62:65], v[92:93], off
	global_load_dwordx2 v[102:103], v[58:59], off
	s_nop 0
	global_load_dwordx4 v[58:61], v[94:95], off
	global_load_dword v124, v[148:149], off offset:576
	global_load_dword v123, v[148:149], off offset:640
	global_load_dword v122, v[148:149], off offset:704
	global_load_dwordx2 v[108:109], v[96:97], off
	s_nop 0
	global_load_dwordx4 v[90:93], v[92:93], off offset:256
	s_nop 0
	global_load_dwordx2 v[104:105], v[104:105], off
	s_nop 0
	global_load_dwordx4 v[94:97], v[94:95], off offset:256
	s_waitcnt vmcnt(13)
	v_mul_f32_e32 v128, 0x3fb504f3, v101
	s_waitcnt vmcnt(12)
	v_mul_f32_e32 v126, v151, v107
	s_waitcnt vmcnt(11)
	v_cvt_f32_f16_sdwa v101, v82 dst_sel:DWORD dst_unused:UNUSED_PAD src0_sel:WORD_1
	v_cvt_f32_f16_e32 v107, v82
	v_cvt_f32_f16_sdwa v125, v83 dst_sel:DWORD dst_unused:UNUSED_PAD src0_sel:WORD_1
	v_cvt_f32_f16_e32 v82, v83
	v_cvt_f32_f16_sdwa v127, v84 dst_sel:DWORD dst_unused:UNUSED_PAD src0_sel:WORD_1
	v_cvt_f32_f16_e32 v129, v84
	v_cvt_f32_f16_sdwa v149, v85 dst_sel:DWORD dst_unused:UNUSED_PAD src0_sel:WORD_1
	v_cvt_f32_f16_e32 v148, v85
	v_pk_mul_f32 v[72:73], v[240:241], s[90:91] op_sel_hi:[1,0]
	v_pk_mul_f32 v[70:71], v[238:239], s[90:91] op_sel_hi:[1,0]
	v_pk_mul_f32 v[68:69], v[236:237], s[90:91] op_sel_hi:[1,0]
	v_pk_mul_f32 v[66:67], v[234:235], s[90:91] op_sel_hi:[1,0]
	s_waitcnt vmcnt(11)
	v_pk_mul_f32 v[80:81], v[128:129], v[248:249] op_sel_hi:[0,1]
	v_pk_mul_f32 v[78:79], v[128:129], v[246:247] op_sel_hi:[0,1]
	s_waitcnt vmcnt(11)
	v_pk_mul_f32 v[76:77], v[128:129], v[244:245] op_sel_hi:[0,1]
	v_pk_mul_f32 v[74:75], v[128:129], v[242:243] op_sel_hi:[0,1]
	v_sub_f32_e32 v82, v82, v100
	v_sub_f32_e32 v83, v125, v100
	v_sub_f32_e32 v84, v107, v100
	v_sub_f32_e32 v85, v101, v100
	v_sub_f32_e32 v148, v148, v100
	v_sub_f32_e32 v149, v149, v100
	v_sub_f32_e32 v152, v129, v100
	v_sub_f32_e32 v153, v127, v100
	v_pk_fma_f32 v[70:71], v[84:85], v[78:79], v[70:71]
	v_pk_fma_f32 v[72:73], v[82:83], v[80:81], v[72:73]
	v_pk_fma_f32 v[66:67], v[152:153], v[74:75], v[66:67]
	v_pk_fma_f32 v[68:69], v[148:149], v[76:77], v[68:69]
	v_pk_fma_f32 v[72:73], v[126:127], v[118:119], v[72:73] op_sel_hi:[0,1,1]
	v_pk_fma_f32 v[70:71], v[126:127], v[114:115], v[70:71] op_sel_hi:[0,1,1]
	v_pk_fma_f32 v[74:75], v[126:127], v[120:121], v[68:69] op_sel_hi:[0,1,1]
	v_pk_fma_f32 v[68:69], v[126:127], v[116:117], v[66:67] op_sel_hi:[0,1,1]
	v_cvt_pk_f16_f32 v66, v70, v71
	v_cvt_pk_f16_f32 v67, v72, v73
	v_cvt_pk_f16_f32 v68, v68, v69
	v_cvt_pk_f16_f32 v69, v74, v75
	global_store_dwordx4 v[112:113], v[66:69], off
	global_load_dwordx4 v[66:69], v[142:143], off offset:512
	s_nop 0
	global_load_dwordx4 v[70:73], v[142:143], off offset:528
	global_load_dwordx4 v[74:77], v[140:141], off offset:512
	global_load_dwordx4 v[78:81], v[140:141], off offset:528
	s_waitcnt vmcnt(15)
	v_cvt_f32_f16_sdwa v85, v86 dst_sel:DWORD dst_unused:UNUSED_PAD src0_sel:WORD_1
	v_cvt_f32_f16_e32 v84, v86
	v_cvt_f32_f16_sdwa v83, v87 dst_sel:DWORD dst_unused:UNUSED_PAD src0_sel:WORD_1
	v_cvt_f32_f16_e32 v82, v87
	v_cvt_f32_f16_sdwa v101, v88 dst_sel:DWORD dst_unused:UNUSED_PAD src0_sel:WORD_1
	v_cvt_f32_f16_e32 v88, v88
	v_cvt_f32_f16_sdwa v87, v89 dst_sel:DWORD dst_unused:UNUSED_PAD src0_sel:WORD_1
	v_cvt_f32_f16_e32 v86, v89
	v_sub_f32_e32 v82, v82, v100
	v_sub_f32_e32 v83, v83, v100
	v_sub_f32_e32 v84, v84, v100
	v_sub_f32_e32 v85, v85, v100
	v_sub_f32_e32 v86, v86, v100
	v_sub_f32_e32 v87, v87, v100
	v_sub_f32_e32 v88, v88, v100
	v_sub_f32_e32 v89, v101, v100
	v_ashrrev_i32_e32 v107, 31, v106
	s_waitcnt vmcnt(3)
; __device__ __forceinline__ u32x4 pk8h(const f32x4 a, const f32x4 b) { u32x4 w; w.x = pkh(a[0], a[1]); w.y = pkh(a[2], a[3]); w.z = pkh(b[0], b[1]); w.w = pkh(b[2], b[3]); return w; }
; __device__ __forceinline__ f32x4 h4lo(const u32x4 w) { return (f32x4){hlo(w.x), hhi(w.x), hlo(w.y), hhi(w.y)}; }
; __device__ __forceinline__ f32x4 h4hi(const u32x4 w) { return (f32x4){hlo(w.z), hhi(w.z), hlo(w.w), hhi(w.w)}; }
;     __device__ __forceinline__ void operator()(const i32x4 (&acc)[2][2][4][2], const Unit& u, int wr, int wc, int fr, int fq) const {
;     ...
;             for (int m = 0; m < 4; ++m) { const int row = row0 + ai * HALF + m * 16; const bf16_t* yp = X + (size_t)row * 4096 + col0; y[m][0] = *(const u32x4*)yp; y[m][1] = *(const u32x4*)(yp + HALF);
;                 mean[m] = stats[2 * row]; rstd[m] = stats[2 * row + 1]; f[m] = rowinv[row] * wdq; }
; #pragma unroll
;             for (int m = 0; m < 4; ++m) { bf16_t* rowp = X + (size_t)(row0 + ai * HALF + m * 16) * 4096 + col0;
; #pragma unroll
;                 for (int bj = 0; bj < 2; ++bj) { const int c = col0 + bj * HALF; const float ra = rstd[m] * alpha;
;                     const f32x4 g0 = *(const f32x4*)(g + c) * ra, g1 = *(const f32x4*)(g + c + 4) * ra, b0 = *(const f32x4*)(b + c) * alpha, b1 = *(const f32x4*)(b + c + 4) * alpha;
;                     const i32x4 a0 = acc[ai][bj][m][0], a1 = acc[ai][bj][m][1];
;                     f32x4 q0, q1; q0.x = (float)a0.x; q0.y = (float)a0.y; q0.z = (float)a0.z; q0.w = (float)a0.w; q1.x = (float)a1.x; q1.y = (float)a1.y; q1.z = (float)a1.z; q1.w = (float)a1.w;
;                     *(u32x4*)(rowp + bj * HALF) = pk8h((h4lo(y[m][bj]) - mean[m]) * g0 + b0 + q0 * f[m], (h4hi(y[m][bj]) - mean[m]) * g1 + b1 + q1 * f[m]); } }
	v_pk_mul_f32 v[68:69], v[128:129], v[68:69] op_sel_hi:[0,1]
	v_pk_mul_f32 v[66:67], v[128:129], v[66:67] op_sel_hi:[0,1]
	s_waitcnt vmcnt(2)
	v_pk_mul_f32 v[72:73], v[128:129], v[72:73] op_sel_hi:[0,1]
	v_pk_mul_f32 v[70:71], v[128:129], v[70:71] op_sel_hi:[0,1]
	s_waitcnt vmcnt(1)
	v_pk_mul_f32 v[76:77], v[76:77], s[90:91] op_sel_hi:[1,0]
	v_pk_mul_f32 v[74:75], v[74:75], s[90:91] op_sel_hi:[1,0]
	s_waitcnt vmcnt(0)
	v_pk_mul_f32 v[80:81], v[80:81], s[90:91] op_sel_hi:[1,0]
	v_pk_mul_f32 v[78:79], v[78:79], s[90:91] op_sel_hi:[1,0]
	v_pk_fma_f32 v[66:67], v[84:85], v[66:67], v[74:75]
	v_pk_fma_f32 v[68:69], v[82:83], v[68:69], v[76:77]
	v_pk_fma_f32 v[70:71], v[88:89], v[70:71], v[78:79]
	v_pk_fma_f32 v[72:73], v[86:87], v[72:73], v[80:81]
	v_pk_fma_f32 v[56:57], v[126:127], v[56:57], v[68:69] op_sel_hi:[0,1,1]
	v_pk_fma_f32 v[54:55], v[126:127], v[54:55], v[66:67] op_sel_hi:[0,1,1]
	v_pk_fma_f32 v[66:67], v[126:127], v[52:53], v[72:73] op_sel_hi:[0,1,1]
	v_pk_fma_f32 v[52:53], v[126:127], v[50:51], v[70:71] op_sel_hi:[0,1,1]
	v_cvt_pk_f16_f32 v50, v54, v55
	v_cvt_pk_f16_f32 v51, v56, v57
	v_cvt_pk_f16_f32 v52, v52, v53
	v_cvt_pk_f16_f32 v53, v66, v67
	global_store_dwordx4 v[112:113], v[50:53], off offset:256
	s_nop 0
	v_cvt_f32_f16_sdwa v77, v62 dst_sel:DWORD dst_unused:UNUSED_PAD src0_sel:WORD_1
	v_cvt_f32_f16_e32 v79, v62
	v_cvt_f32_f16_sdwa v80, v63 dst_sel:DWORD dst_unused:UNUSED_PAD src0_sel:WORD_1
	v_cvt_f32_f16_e32 v62, v63
	v_cvt_f32_f16_sdwa v83, v64 dst_sel:DWORD dst_unused:UNUSED_PAD src0_sel:WORD_1
	v_cvt_f32_f16_e32 v82, v64
	v_cvt_f32_f16_sdwa v81, v65 dst_sel:DWORD dst_unused:UNUSED_PAD src0_sel:WORD_1
	v_cvt_f32_f16_e32 v84, v65
	v_mul_f32_e32 v78, 0x3fb504f3, v109
	v_sub_f32_e32 v62, v62, v108
	v_sub_f32_e32 v63, v80, v108
	v_sub_f32_e32 v64, v79, v108
	v_sub_f32_e32 v65, v77, v108
	v_sub_f32_e32 v80, v84, v108
	v_sub_f32_e32 v81, v81, v108
	v_sub_f32_e32 v82, v82, v108
	v_sub_f32_e32 v83, v83, v108
	v_mul_f32_e32 v76, v151, v124
	v_lshl_add_u64 v[74:75], s[10:11], 0, v[110:111]
	v_lshl_add_u64 v[74:75], v[74:75], 0, v[144:145]
	s_waitcnt vmcnt(0)
	v_pk_mul_f32 v[52:53], v[78:79], v[248:249] op_sel_hi:[0,1]
	v_pk_mul_f32 v[50:51], v[78:79], v[246:247] op_sel_hi:[0,1]
	s_waitcnt vmcnt(0)
	v_pk_mul_f32 v[56:57], v[78:79], v[244:245] op_sel_hi:[0,1]
	v_pk_mul_f32 v[54:55], v[78:79], v[242:243] op_sel_hi:[0,1]
	s_waitcnt vmcnt(0)
	v_pk_mul_f32 v[68:69], v[240:241], s[90:91] op_sel_hi:[1,0]
	v_pk_mul_f32 v[66:67], v[238:239], s[90:91] op_sel_hi:[1,0]
	s_waitcnt vmcnt(0)
	v_pk_mul_f32 v[72:73], v[236:237], s[90:91] op_sel_hi:[1,0]
	v_pk_mul_f32 v[70:71], v[234:235], s[90:91] op_sel_hi:[1,0]
	v_pk_fma_f32 v[50:51], v[64:65], v[50:51], v[66:67]
	v_pk_fma_f32 v[52:53], v[62:63], v[52:53], v[68:69]
	v_pk_fma_f32 v[54:55], v[82:83], v[54:55], v[70:71]
	v_pk_fma_f32 v[56:57], v[80:81], v[56:57], v[72:73]
	v_pk_fma_f32 v[48:49], v[76:77], v[48:49], v[52:53] op_sel_hi:[0,1,1]
	v_pk_fma_f32 v[46:47], v[76:77], v[46:47], v[50:51] op_sel_hi:[0,1,1]
	v_pk_fma_f32 v[50:51], v[76:77], v[44:45], v[56:57] op_sel_hi:[0,1,1]
	v_pk_fma_f32 v[44:45], v[76:77], v[42:43], v[54:55] op_sel_hi:[0,1,1]
	v_cvt_pk_f16_f32 v42, v46, v47
	v_cvt_pk_f16_f32 v43, v48, v49
	v_cvt_pk_f16_f32 v44, v44, v45
	v_cvt_pk_f16_f32 v45, v50, v51
	global_store_dwordx4 v[74:75], v[42:45], off
	global_load_dwordx4 v[42:45], v[142:143], off offset:512
	s_nop 0
	global_load_dwordx4 v[46:49], v[142:143], off offset:528
	global_load_dwordx4 v[50:53], v[140:141], off offset:512
	global_load_dwordx4 v[54:57], v[140:141], off offset:528
	v_cvt_f32_f16_sdwa v73, v90 dst_sel:DWORD dst_unused:UNUSED_PAD src0_sel:WORD_1
	v_cvt_f32_f16_e32 v72, v90
	v_cvt_f32_f16_sdwa v71, v91 dst_sel:DWORD dst_unused:UNUSED_PAD src0_sel:WORD_1
	v_cvt_f32_f16_e32 v70, v91
	v_cvt_f32_f16_sdwa v77, v92 dst_sel:DWORD dst_unused:UNUSED_PAD src0_sel:WORD_1
	v_cvt_f32_f16_e32 v79, v92
	v_cvt_f32_f16_sdwa v81, v93 dst_sel:DWORD dst_unused:UNUSED_PAD src0_sel:WORD_1
	v_cvt_f32_f16_e32 v80, v93
	v_cvt_f32_i32_e32 v63, v35
	v_cvt_f32_i32_e32 v62, v34
	v_cvt_f32_i32_e32 v65, v37
	v_cvt_f32_i32_e32 v64, v36
	v_lshlrev_b64 v[66:67], 13, v[106:107]
	v_lshl_add_u64 v[68:69], v[146:147], 0, v[66:67]
	v_sub_f32_e32 v70, v70, v108
	v_sub_f32_e32 v71, v71, v108
	v_sub_f32_e32 v72, v72, v108
	v_sub_f32_e32 v73, v73, v108
	v_sub_f32_e32 v80, v80, v108
	v_sub_f32_e32 v81, v81, v108
	v_sub_f32_e32 v82, v79, v108
	v_sub_f32_e32 v83, v77, v108
	global_load_dwordx4 v[34:37], v[68:69], off
	s_waitcnt vmcnt(4)
	v_pk_mul_f32 v[44:45], v[78:79], v[44:45] op_sel_hi:[0,1]
	v_pk_mul_f32 v[42:43], v[78:79], v[42:43] op_sel_hi:[0,1]
	s_waitcnt vmcnt(3)
	v_pk_mul_f32 v[48:49], v[78:79], v[48:49] op_sel_hi:[0,1]
	v_pk_mul_f32 v[46:47], v[78:79], v[46:47] op_sel_hi:[0,1]
	s_waitcnt vmcnt(2)
	v_pk_mul_f32 v[52:53], v[52:53], s[90:91] op_sel_hi:[1,0]
	v_pk_mul_f32 v[50:51], v[50:51], s[90:91] op_sel_hi:[1,0]
	s_waitcnt vmcnt(1)
	v_pk_mul_f32 v[56:57], v[56:57], s[90:91] op_sel_hi:[1,0]
	v_pk_mul_f32 v[54:55], v[54:55], s[90:91] op_sel_hi:[1,0]
	v_pk_fma_f32 v[42:43], v[72:73], v[42:43], v[50:51]
	v_pk_fma_f32 v[44:45], v[70:71], v[44:45], v[52:53]
	v_pk_fma_f32 v[46:47], v[82:83], v[46:47], v[54:55]
	v_pk_fma_f32 v[48:49], v[80:81], v[48:49], v[56:57]
	v_pk_fma_f32 v[40:41], v[76:77], v[40:41], v[44:45] op_sel_hi:[0,1,1]
	v_pk_fma_f32 v[38:39], v[76:77], v[38:39], v[42:43] op_sel_hi:[0,1,1]
	v_pk_fma_f32 v[42:43], v[76:77], v[64:65], v[48:49] op_sel_hi:[0,1,1]
	v_pk_fma_f32 v[44:45], v[76:77], v[62:63], v[46:47] op_sel_hi:[0,1,1]
	v_cvt_pk_f16_f32 v38, v38, v39
	v_cvt_pk_f16_f32 v39, v40, v41
	v_cvt_pk_f16_f32 v40, v44, v45
	v_cvt_pk_f16_f32 v41, v42, v43
	global_store_dwordx4 v[74:75], v[38:41], off offset:256
	s_nop 0
	v_cvt_f32_i32_e32 v55, v27
	v_cvt_f32_i32_e32 v54, v26
	v_lshl_add_u64 v[26:27], s[10:11], 0, v[66:67]
	v_cvt_f32_i32_e32 v57, v29
	v_cvt_f32_i32_e32 v56, v28
	v_lshl_add_u64 v[62:63], v[26:27], 0, v[144:145]
	global_load_dwordx4 v[26:29], v[68:69], off offset:256
	s_waitcnt vmcnt(2)
; __device__ __forceinline__ u32x4 pk8h(const f32x4 a, const f32x4 b) { u32x4 w; w.x = pkh(a[0], a[1]); w.y = pkh(a[2], a[3]); w.z = pkh(b[0], b[1]); w.w = pkh(b[2], b[3]); return w; }
; __device__ __forceinline__ f32x4 h4lo(const u32x4 w) { return (f32x4){hlo(w.x), hhi(w.x), hlo(w.y), hhi(w.y)}; }
; __device__ __forceinline__ f32x4 h4hi(const u32x4 w) { return (f32x4){hlo(w.z), hhi(w.z), hlo(w.w), hhi(w.w)}; }
;     __device__ __forceinline__ void operator()(const i32x4 (&acc)[2][2][4][2], const Unit& u, int wr, int wc, int fr, int fq) const {
;     ...
;             for (int m = 0; m < 4; ++m) { const int row = row0 + ai * HALF + m * 16; const bf16_t* yp = X + (size_t)row * 4096 + col0; y[m][0] = *(const u32x4*)yp; y[m][1] = *(const u32x4*)(yp + HALF);
;                 mean[m] = stats[2 * row]; rstd[m] = stats[2 * row + 1]; f[m] = rowinv[row] * wdq; }
; #pragma unroll
;             for (int m = 0; m < 4; ++m) { bf16_t* rowp = X + (size_t)(row0 + ai * HALF + m * 16) * 4096 + col0;
; #pragma unroll
;                 for (int bj = 0; bj < 2; ++bj) { const int c = col0 + bj * HALF; const float ra = rstd[m] * alpha;
;                     const f32x4 g0 = *(const f32x4*)(g + c) * ra, g1 = *(const f32x4*)(g + c + 4) * ra, b0 = *(const f32x4*)(b + c) * alpha, b1 = *(const f32x4*)(b + c + 4) * alpha;
;                     const i32x4 a0 = acc[ai][bj][m][0], a1 = acc[ai][bj][m][1];
;                     f32x4 q0, q1; q0.x = (float)a0.x; q0.y = (float)a0.y; q0.z = (float)a0.z; q0.w = (float)a0.w; q1.x = (float)a1.x; q1.y = (float)a1.y; q1.z = (float)a1.z; q1.w = (float)a1.w;
;                     *(u32x4*)(rowp + bj * HALF) = pk8h((h4lo(y[m][bj]) - mean[m]) * g0 + b0 + q0 * f[m], (h4hi(y[m][bj]) - mean[m]) * g1 + b1 + q1 * f[m]); } }
	v_cvt_f32_f16_sdwa v65, v34 dst_sel:DWORD dst_unused:UNUSED_PAD src0_sel:WORD_1
	v_cvt_f32_f16_e32 v67, v34
	v_cvt_f32_f16_sdwa v68, v35 dst_sel:DWORD dst_unused:UNUSED_PAD src0_sel:WORD_1
	v_cvt_f32_f16_e32 v34, v35
	v_cvt_f32_f16_sdwa v71, v36 dst_sel:DWORD dst_unused:UNUSED_PAD src0_sel:WORD_1
	v_cvt_f32_f16_e32 v70, v36
	v_cvt_f32_f16_sdwa v69, v37 dst_sel:DWORD dst_unused:UNUSED_PAD src0_sel:WORD_1
	v_cvt_f32_f16_e32 v72, v37
	v_mul_f32_e32 v66, 0x3fb504f3, v103
	v_sub_f32_e32 v34, v34, v102
	v_sub_f32_e32 v35, v68, v102
	v_sub_f32_e32 v36, v67, v102
	v_sub_f32_e32 v37, v65, v102
	v_sub_f32_e32 v68, v72, v102
	v_sub_f32_e32 v69, v69, v102
	v_sub_f32_e32 v70, v70, v102
	v_sub_f32_e32 v71, v71, v102
	v_mul_f32_e32 v64, v151, v123
	s_waitcnt vmcnt(1)
	v_pk_mul_f32 v[40:41], v[66:67], v[248:249] op_sel_hi:[0,1]
	v_pk_mul_f32 v[38:39], v[66:67], v[246:247] op_sel_hi:[0,1]
	s_waitcnt vmcnt(1)
	v_pk_mul_f32 v[44:45], v[66:67], v[244:245] op_sel_hi:[0,1]
	v_pk_mul_f32 v[42:43], v[66:67], v[242:243] op_sel_hi:[0,1]
	s_waitcnt vmcnt(1)
	v_pk_mul_f32 v[48:49], v[240:241], s[90:91] op_sel_hi:[1,0]
	v_pk_mul_f32 v[46:47], v[238:239], s[90:91] op_sel_hi:[1,0]
	s_waitcnt vmcnt(1)
	v_pk_mul_f32 v[52:53], v[236:237], s[90:91] op_sel_hi:[1,0]
	v_pk_mul_f32 v[50:51], v[234:235], s[90:91] op_sel_hi:[1,0]
	v_pk_fma_f32 v[36:37], v[36:37], v[38:39], v[46:47]
	v_pk_fma_f32 v[34:35], v[34:35], v[40:41], v[48:49]
	v_pk_fma_f32 v[38:39], v[70:71], v[42:43], v[50:51]
	v_pk_fma_f32 v[40:41], v[68:69], v[44:45], v[52:53]
	v_pk_fma_f32 v[32:33], v[64:65], v[32:33], v[34:35] op_sel_hi:[0,1,1]
	v_pk_fma_f32 v[30:31], v[64:65], v[30:31], v[36:37] op_sel_hi:[0,1,1]
	v_pk_fma_f32 v[34:35], v[64:65], v[56:57], v[40:41] op_sel_hi:[0,1,1]
	v_pk_fma_f32 v[36:37], v[64:65], v[54:55], v[38:39] op_sel_hi:[0,1,1]
	v_cvt_pk_f16_f32 v30, v30, v31
	v_cvt_pk_f16_f32 v31, v32, v33
	v_cvt_pk_f16_f32 v32, v36, v37
	v_cvt_pk_f16_f32 v33, v34, v35
	global_store_dwordx4 v[62:63], v[30:33], off
	global_load_dwordx4 v[30:33], v[142:143], off offset:512
	s_nop 0
	global_load_dwordx4 v[34:37], v[142:143], off offset:528
	global_load_dwordx4 v[38:41], v[140:141], off offset:512
	global_load_dwordx4 v[42:45], v[140:141], off offset:528
	s_waitcnt vmcnt(5)
	v_cvt_f32_f16_sdwa v46, v26 dst_sel:DWORD dst_unused:UNUSED_PAD src0_sel:WORD_1
	v_cvt_f32_f16_e32 v47, v26
	v_cvt_f32_f16_sdwa v48, v27 dst_sel:DWORD dst_unused:UNUSED_PAD src0_sel:WORD_1
	v_cvt_f32_f16_e32 v26, v27
	v_cvt_f32_f16_sdwa v49, v28 dst_sel:DWORD dst_unused:UNUSED_PAD src0_sel:WORD_1
	v_cvt_f32_f16_e32 v50, v28
	v_cvt_f32_f16_sdwa v51, v29 dst_sel:DWORD dst_unused:UNUSED_PAD src0_sel:WORD_1
	v_cvt_f32_f16_e32 v52, v29
	v_sub_f32_e32 v26, v26, v102
	v_sub_f32_e32 v27, v48, v102
	v_sub_f32_e32 v28, v47, v102
	v_sub_f32_e32 v29, v46, v102
	v_sub_f32_e32 v46, v52, v102
	v_sub_f32_e32 v47, v51, v102
	v_sub_f32_e32 v48, v50, v102
	v_sub_f32_e32 v49, v49, v102
	s_waitcnt vmcnt(3)
	v_pk_mul_f32 v[32:33], v[66:67], v[32:33] op_sel_hi:[0,1]
	v_pk_mul_f32 v[30:31], v[66:67], v[30:31] op_sel_hi:[0,1]
	s_waitcnt vmcnt(2)
	v_pk_mul_f32 v[36:37], v[66:67], v[36:37] op_sel_hi:[0,1]
	v_pk_mul_f32 v[34:35], v[66:67], v[34:35] op_sel_hi:[0,1]
	s_waitcnt vmcnt(1)
	v_pk_mul_f32 v[40:41], v[40:41], s[90:91] op_sel_hi:[1,0]
	v_pk_mul_f32 v[38:39], v[38:39], s[90:91] op_sel_hi:[1,0]
	s_waitcnt vmcnt(0)
	v_pk_mul_f32 v[44:45], v[44:45], s[90:91] op_sel_hi:[1,0]
	v_pk_mul_f32 v[42:43], v[42:43], s[90:91] op_sel_hi:[1,0]
	v_pk_fma_f32 v[28:29], v[28:29], v[30:31], v[38:39]
	v_pk_fma_f32 v[26:27], v[26:27], v[32:33], v[40:41]
	v_pk_fma_f32 v[30:31], v[48:49], v[34:35], v[42:43]
	v_pk_fma_f32 v[32:33], v[46:47], v[36:37], v[44:45]
	v_pk_fma_f32 v[24:25], v[64:65], v[24:25], v[26:27] op_sel_hi:[0,1,1]
	v_pk_fma_f32 v[22:23], v[64:65], v[22:23], v[28:29] op_sel_hi:[0,1,1]
	v_pk_fma_f32 v[26:27], v[64:65], v[20:21], v[32:33] op_sel_hi:[0,1,1]
	v_pk_fma_f32 v[20:21], v[64:65], v[18:19], v[30:31] op_sel_hi:[0,1,1]
	v_cvt_pk_f16_f32 v18, v22, v23
	v_cvt_pk_f16_f32 v19, v24, v25
	v_cvt_pk_f16_f32 v20, v20, v21
	v_cvt_pk_f16_f32 v21, v26, v27
	global_store_dwordx4 v[62:63], v[18:21], off offset:256
	s_nop 0
	v_cvt_f32_f16_sdwa v37, v58 dst_sel:DWORD dst_unused:UNUSED_PAD src0_sel:WORD_1
	v_cvt_f32_f16_e32 v39, v58
	v_cvt_f32_f16_sdwa v41, v59 dst_sel:DWORD dst_unused:UNUSED_PAD src0_sel:WORD_1
	v_cvt_f32_f16_e32 v40, v59
	v_cvt_f32_f16_sdwa v47, v60 dst_sel:DWORD dst_unused:UNUSED_PAD src0_sel:WORD_1
	v_cvt_f32_f16_e32 v46, v60
	v_cvt_f32_f16_sdwa v45, v61 dst_sel:DWORD dst_unused:UNUSED_PAD src0_sel:WORD_1
	v_cvt_f32_f16_e32 v44, v61
	v_mul_f32_e32 v38, 0x3fb504f3, v105
	v_sub_f32_e32 v40, v40, v104
	v_sub_f32_e32 v41, v41, v104
	v_sub_f32_e32 v42, v39, v104
	v_sub_f32_e32 v43, v37, v104
	v_sub_f32_e32 v44, v44, v104
	v_sub_f32_e32 v45, v45, v104
	v_sub_f32_e32 v46, v46, v104
	v_sub_f32_e32 v47, v47, v104
	v_mul_f32_e32 v36, v151, v122
	v_lshl_add_u64 v[34:35], s[10:11], 0, v[98:99]
	v_lshl_add_u64 v[34:35], v[34:35], 0, v[144:145]
	s_waitcnt vmcnt(0)
; __device__ __forceinline__ u32x4 pk8h(const f32x4 a, const f32x4 b) { u32x4 w; w.x = pkh(a[0], a[1]); w.y = pkh(a[2], a[3]); w.z = pkh(b[0], b[1]); w.w = pkh(b[2], b[3]); return w; }
; __device__ __forceinline__ f32x4 h4lo(const u32x4 w) { return (f32x4){hlo(w.x), hhi(w.x), hlo(w.y), hhi(w.y)}; }
; __device__ __forceinline__ f32x4 h4hi(const u32x4 w) { return (f32x4){hlo(w.z), hhi(w.z), hlo(w.w), hhi(w.w)}; }
;     __device__ __forceinline__ void operator()(const i32x4 (&acc)[2][2][4][2], const Unit& u, int wr, int wc, int fr, int fq) const {
;     ...
;             for (int m = 0; m < 4; ++m) { const int row = row0 + ai * HALF + m * 16; const bf16_t* yp = X + (size_t)row * 4096 + col0; y[m][0] = *(const u32x4*)yp; y[m][1] = *(const u32x4*)(yp + HALF);
;                 mean[m] = stats[2 * row]; rstd[m] = stats[2 * row + 1]; f[m] = rowinv[row] * wdq; }
; #pragma unroll
;             for (int m = 0; m < 4; ++m) { bf16_t* rowp = X + (size_t)(row0 + ai * HALF + m * 16) * 4096 + col0;
; #pragma unroll
;                 for (int bj = 0; bj < 2; ++bj) { const int c = col0 + bj * HALF; const float ra = rstd[m] * alpha;
;                     const f32x4 g0 = *(const f32x4*)(g + c) * ra, g1 = *(const f32x4*)(g + c + 4) * ra, b0 = *(const f32x4*)(b + c) * alpha, b1 = *(const f32x4*)(b + c + 4) * alpha;
;                     const i32x4 a0 = acc[ai][bj][m][0], a1 = acc[ai][bj][m][1];
;                     f32x4 q0, q1; q0.x = (float)a0.x; q0.y = (float)a0.y; q0.z = (float)a0.z; q0.w = (float)a0.w; q1.x = (float)a1.x; q1.y = (float)a1.y; q1.z = (float)a1.z; q1.w = (float)a1.w;
;                     *(u32x4*)(rowp + bj * HALF) = pk8h((h4lo(y[m][bj]) - mean[m]) * g0 + b0 + q0 * f[m], (h4hi(y[m][bj]) - mean[m]) * g1 + b1 + q1 * f[m]); } }
;             asm volatile("" ::: "memory");
;         }
	v_pk_mul_f32 v[20:21], v[38:39], v[248:249] op_sel_hi:[0,1]
	v_pk_mul_f32 v[18:19], v[38:39], v[246:247] op_sel_hi:[0,1]
	s_waitcnt vmcnt(0)
	v_pk_mul_f32 v[24:25], v[38:39], v[244:245] op_sel_hi:[0,1]
	v_pk_mul_f32 v[22:23], v[38:39], v[242:243] op_sel_hi:[0,1]
	s_waitcnt vmcnt(0)
	v_pk_mul_f32 v[28:29], v[240:241], s[90:91] op_sel_hi:[1,0]
	v_pk_mul_f32 v[26:27], v[238:239], s[90:91] op_sel_hi:[1,0]
	s_waitcnt vmcnt(0)
	v_pk_mul_f32 v[32:33], v[236:237], s[90:91] op_sel_hi:[1,0]
	v_pk_mul_f32 v[30:31], v[234:235], s[90:91] op_sel_hi:[1,0]
	v_pk_fma_f32 v[18:19], v[42:43], v[18:19], v[26:27]
	v_pk_fma_f32 v[20:21], v[40:41], v[20:21], v[28:29]
	v_pk_fma_f32 v[22:23], v[46:47], v[22:23], v[30:31]
	v_pk_fma_f32 v[24:25], v[44:45], v[24:25], v[32:33]
	v_pk_fma_f32 v[16:17], v[36:37], v[16:17], v[20:21] op_sel_hi:[0,1,1]
	v_pk_fma_f32 v[14:15], v[36:37], v[14:15], v[18:19] op_sel_hi:[0,1,1]
	v_pk_fma_f32 v[18:19], v[36:37], v[12:13], v[24:25] op_sel_hi:[0,1,1]
	v_pk_fma_f32 v[12:13], v[36:37], v[10:11], v[22:23] op_sel_hi:[0,1,1]
	v_cvt_pk_f16_f32 v10, v14, v15
	v_cvt_pk_f16_f32 v11, v16, v17
	v_cvt_pk_f16_f32 v12, v12, v13
	v_cvt_pk_f16_f32 v13, v18, v19
	global_store_dwordx4 v[34:35], v[10:13], off
	global_load_dwordx4 v[10:13], v[142:143], off offset:512
	s_nop 0
	global_load_dwordx4 v[14:17], v[142:143], off offset:528
	global_load_dwordx4 v[18:21], v[140:141], off offset:512
	global_load_dwordx4 v[22:25], v[140:141], off offset:528
	v_cvt_f32_f16_sdwa v29, v94 dst_sel:DWORD dst_unused:UNUSED_PAD src0_sel:WORD_1
	v_cvt_f32_f16_e32 v28, v94
	v_cvt_f32_f16_sdwa v27, v95 dst_sel:DWORD dst_unused:UNUSED_PAD src0_sel:WORD_1
	v_cvt_f32_f16_e32 v26, v95
	v_cvt_f32_f16_sdwa v33, v96 dst_sel:DWORD dst_unused:UNUSED_PAD src0_sel:WORD_1
	v_cvt_f32_f16_e32 v32, v96
	v_cvt_f32_f16_sdwa v31, v97 dst_sel:DWORD dst_unused:UNUSED_PAD src0_sel:WORD_1
	v_cvt_f32_f16_e32 v30, v97
	v_sub_f32_e32 v26, v26, v104
	v_sub_f32_e32 v27, v27, v104
	v_sub_f32_e32 v28, v28, v104
	v_sub_f32_e32 v29, v29, v104
	v_sub_f32_e32 v30, v30, v104
	v_sub_f32_e32 v31, v31, v104
	v_sub_f32_e32 v32, v32, v104
	v_sub_f32_e32 v33, v33, v104
	s_waitcnt vmcnt(3)
	v_pk_mul_f32 v[12:13], v[38:39], v[12:13] op_sel_hi:[0,1]
	v_pk_mul_f32 v[10:11], v[38:39], v[10:11] op_sel_hi:[0,1]
	s_waitcnt vmcnt(2)
	v_pk_mul_f32 v[16:17], v[38:39], v[16:17] op_sel_hi:[0,1]
	v_pk_mul_f32 v[14:15], v[38:39], v[14:15] op_sel_hi:[0,1]
	s_waitcnt vmcnt(1)
	v_pk_mul_f32 v[20:21], v[20:21], s[90:91] op_sel_hi:[1,0]
	v_pk_mul_f32 v[18:19], v[18:19], s[90:91] op_sel_hi:[1,0]
	s_waitcnt vmcnt(0)
	v_pk_mul_f32 v[24:25], v[24:25], s[90:91] op_sel_hi:[1,0]
	v_pk_mul_f32 v[22:23], v[22:23], s[90:91] op_sel_hi:[1,0]
	v_pk_fma_f32 v[10:11], v[28:29], v[10:11], v[18:19]
	v_pk_fma_f32 v[12:13], v[26:27], v[12:13], v[20:21]
	v_pk_fma_f32 v[14:15], v[32:33], v[14:15], v[22:23]
	v_pk_fma_f32 v[16:17], v[30:31], v[16:17], v[24:25]
	v_pk_fma_f32 v[8:9], v[36:37], v[8:9], v[12:13] op_sel_hi:[0,1,1]
	v_pk_fma_f32 v[6:7], v[36:37], v[6:7], v[10:11] op_sel_hi:[0,1,1]
	v_pk_fma_f32 v[10:11], v[36:37], v[4:5], v[16:17] op_sel_hi:[0,1,1]
	v_pk_fma_f32 v[4:5], v[36:37], v[2:3], v[14:15] op_sel_hi:[0,1,1]
	v_cvt_pk_f16_f32 v2, v6, v7
	v_cvt_pk_f16_f32 v3, v8, v9
	v_cvt_pk_f16_f32 v4, v4, v5
	v_cvt_pk_f16_f32 v5, v10, v11
	global_store_dwordx4 v[34:35], v[2:5], off offset:256
	s_cbranch_vccnz .LBB0_1192
	s_andn2_b64 vcc, exec, s[8:9]
	s_cbranch_vccnz .LBB0_1191
	s_barrier
	s_branch .LBB0_1191
